# half-height GEMM0 tile loop also uses the spread slot-table schedule (loads, LDS writes and next-step fragment reads interleaved across all 16 MFMAs)
# speedup vs baseline: 1.0230x; 1.0042x over previous
.Lgq_h:
	ds_read_b128 v[74:77], v188 offset:16384
	ds_read_b128 v[78:81], v188 offset:16896
	ds_read_b128 v[90:93], v188 offset:20480
	ds_read_b128 v[94:97], v188 offset:20992
	ds_read_b128 v[82:85], v71
	ds_read_b128 v[86:89], v71 offset:2048
	s_waitcnt lgkmcnt(1)
	v_mfma_f32_16x16x32_bf16 v[30:33], v[74:77], v[82:85], v[30:33]
	ds_read_b128 v[164:167], v189 offset:16384
	ds_read_b128 v[168:171], v189 offset:16896
	global_load_dwordx4 v[34:37], v216, s[0:1] offset:256
	v_mfma_f32_16x16x32_bf16 v[26:29], v[78:81], v[82:85], v[26:29]
	s_waitcnt vmcnt(6)
	ds_write_b128 v69, v[224:227] offset:32768
	v_mfma_f32_16x16x32_bf16 v[22:25], v[90:93], v[82:85], v[22:25]
	ds_read_b128 v[172:175], v189 offset:20480
	ds_read_b128 v[176:179], v189 offset:20992
	v_mfma_f32_16x16x32_bf16 v[18:21], v[94:97], v[82:85], v[18:21]
	global_load_dwordx4 v[46:49], v217, s[0:1] offset:256
	s_waitcnt lgkmcnt(5)
	v_mfma_f32_16x16x32_bf16 v[14:17], v[74:77], v[86:89], v[14:17]
	ds_read_b128 v[180:183], v72
	ds_read_b128 v[184:187], v72 offset:2048
	s_waitcnt vmcnt(6)
	ds_write_b128 v69, v[228:231] offset:36864
	v_mfma_f32_16x16x32_bf16 v[10:13], v[78:81], v[86:89], v[10:13]
	global_load_dwordx4 v[38:41], v216, s[6:7] offset:256
	v_mfma_f32_16x16x32_bf16 v[6:9], v[90:93], v[86:89], v[6:9]
	s_waitcnt vmcnt(6)
	ds_write_b128 v190, v[232:235] offset:49168
	v_mfma_f32_16x16x32_bf16 v[2:5], v[94:97], v[86:89], v[2:5]
	s_waitcnt lgkmcnt(3)
	v_mfma_f32_16x16x32_bf16 v[30:33], v[164:167], v[180:183], v[30:33]
	global_load_dwordx4 v[42:45], v217, s[6:7] offset:256
	v_mfma_f32_16x16x32_bf16 v[26:29], v[168:171], v[180:183], v[26:29]
	s_waitcnt vmcnt(6)
	ds_write_b128 v190, v[236:239] offset:53264
	v_mfma_f32_16x16x32_bf16 v[22:25], v[172:175], v[180:183], v[22:25]
	global_load_dwordx4 v[50:53], v218, s[6:7] offset:256
	v_mfma_f32_16x16x32_bf16 v[18:21], v[176:179], v[180:183], v[18:21]
	s_waitcnt vmcnt(6)
	ds_write_b128 v190, v[240:243] offset:57360
	s_waitcnt lgkmcnt(4)
	v_mfma_f32_16x16x32_bf16 v[14:17], v[164:167], v[184:187], v[14:17]
	global_load_dwordx4 v[54:57], v219, s[6:7] offset:256
	v_mfma_f32_16x16x32_bf16 v[10:13], v[168:171], v[184:187], v[10:13]
	s_waitcnt vmcnt(6)
	ds_write_b128 v190, v[244:247] offset:61456
	v_mfma_f32_16x16x32_bf16 v[6:9], v[172:175], v[184:187], v[6:9]
	v_mfma_f32_16x16x32_bf16 v[2:5], v[176:179], v[184:187], v[2:5]
	s_waitcnt lgkmcnt(0)
	s_barrier
	s_add_u32 s0, s0, 0x80
	s_addc_u32 s1, s1, 0
	s_add_u32 s6, s6, 0x80
	s_addc_u32 s7, s7, 0
	ds_read_b128 v[74:77], v188 offset:49168
	ds_read_b128 v[78:81], v188 offset:49680
	ds_read_b128 v[90:93], v188 offset:53264
	ds_read_b128 v[94:97], v188 offset:53776
	ds_read_b128 v[82:85], v71 offset:32768
	ds_read_b128 v[86:89], v71 offset:34816
	s_waitcnt lgkmcnt(1)
	v_mfma_f32_16x16x32_bf16 v[30:33], v[74:77], v[82:85], v[30:33]
	ds_read_b128 v[164:167], v189 offset:49168
	ds_read_b128 v[168:171], v189 offset:49680
	global_load_dwordx4 v[224:227], v216, s[0:1] offset:256
	v_mfma_f32_16x16x32_bf16 v[26:29], v[78:81], v[82:85], v[26:29]
	s_waitcnt vmcnt(6)
	ds_write_b128 v69, v[34:37]
	v_mfma_f32_16x16x32_bf16 v[22:25], v[90:93], v[82:85], v[22:25]
	ds_read_b128 v[172:175], v189 offset:53264
	ds_read_b128 v[176:179], v189 offset:53776
	v_mfma_f32_16x16x32_bf16 v[18:21], v[94:97], v[82:85], v[18:21]
	global_load_dwordx4 v[228:231], v217, s[0:1] offset:256
	s_waitcnt lgkmcnt(5)
	v_mfma_f32_16x16x32_bf16 v[14:17], v[74:77], v[86:89], v[14:17]
	ds_read_b128 v[180:183], v72 offset:32768
	ds_read_b128 v[184:187], v72 offset:34816
	s_waitcnt vmcnt(6)
	ds_write_b128 v69, v[46:49] offset:4096
	v_mfma_f32_16x16x32_bf16 v[10:13], v[78:81], v[86:89], v[10:13]
	global_load_dwordx4 v[232:235], v216, s[6:7] offset:256
	v_mfma_f32_16x16x32_bf16 v[6:9], v[90:93], v[86:89], v[6:9]
	s_waitcnt vmcnt(6)
	ds_write_b128 v190, v[38:41] offset:16384
	v_mfma_f32_16x16x32_bf16 v[2:5], v[94:97], v[86:89], v[2:5]
	s_waitcnt lgkmcnt(3)
	v_mfma_f32_16x16x32_bf16 v[30:33], v[164:167], v[180:183], v[30:33]
	global_load_dwordx4 v[236:239], v217, s[6:7] offset:256
	v_mfma_f32_16x16x32_bf16 v[26:29], v[168:171], v[180:183], v[26:29]
	s_waitcnt vmcnt(6)
	ds_write_b128 v190, v[42:45] offset:20480
	v_mfma_f32_16x16x32_bf16 v[22:25], v[172:175], v[180:183], v[22:25]
	global_load_dwordx4 v[240:243], v218, s[6:7] offset:256
	v_mfma_f32_16x16x32_bf16 v[18:21], v[176:179], v[180:183], v[18:21]
	s_waitcnt vmcnt(6)
	ds_write_b128 v190, v[50:53] offset:24576
	s_waitcnt lgkmcnt(4)
	v_mfma_f32_16x16x32_bf16 v[14:17], v[164:167], v[184:187], v[14:17]
	global_load_dwordx4 v[244:247], v219, s[6:7] offset:256
	v_mfma_f32_16x16x32_bf16 v[10:13], v[168:171], v[184:187], v[10:13]
	s_waitcnt vmcnt(6)
	ds_write_b128 v190, v[54:57] offset:28672
	v_mfma_f32_16x16x32_bf16 v[6:9], v[172:175], v[184:187], v[6:9]
	v_mfma_f32_16x16x32_bf16 v[2:5], v[176:179], v[184:187], v[2:5]
	s_waitcnt lgkmcnt(0)
	s_barrier
	s_add_u32 s0, s0, 0x80
	s_addc_u32 s1, s1, 0
	s_add_u32 s6, s6, 0x80
	s_addc_u32 s7, s7, 0
	s_sub_i32 vcc_lo, vcc_lo, 1
	s_cmp_lg_u32 vcc_lo, 0
	s_cbranch_scc1 .Lgq_h
	ds_read_b128 v[74:77], v188 offset:16384
	ds_read_b128 v[78:81], v188 offset:16896
	ds_read_b128 v[90:93], v188 offset:20480
	ds_read_b128 v[94:97], v188 offset:20992
	ds_read_b128 v[82:85], v71
	ds_read_b128 v[86:89], v71 offset:2048
	s_waitcnt lgkmcnt(1)
	v_mfma_f32_16x16x32_bf16 v[30:33], v[74:77], v[82:85], v[30:33]
	ds_read_b128 v[164:167], v189 offset:16384
	ds_read_b128 v[168:171], v189 offset:16896
	v_mfma_f32_16x16x32_bf16 v[26:29], v[78:81], v[82:85], v[26:29]
	s_waitcnt vmcnt(5)
	ds_write_b128 v69, v[224:227] offset:32768
	v_mfma_f32_16x16x32_bf16 v[22:25], v[90:93], v[82:85], v[22:25]
	ds_read_b128 v[172:175], v189 offset:20480
	ds_read_b128 v[176:179], v189 offset:20992
	v_mfma_f32_16x16x32_bf16 v[18:21], v[94:97], v[82:85], v[18:21]
	s_waitcnt lgkmcnt(5)
	v_mfma_f32_16x16x32_bf16 v[14:17], v[74:77], v[86:89], v[14:17]
	ds_read_b128 v[180:183], v72
	ds_read_b128 v[184:187], v72 offset:2048
	s_waitcnt vmcnt(4)
	ds_write_b128 v69, v[228:231] offset:36864
	v_mfma_f32_16x16x32_bf16 v[10:13], v[78:81], v[86:89], v[10:13]
	v_mfma_f32_16x16x32_bf16 v[6:9], v[90:93], v[86:89], v[6:9]
	s_waitcnt vmcnt(3)
	ds_write_b128 v190, v[232:235] offset:49168
	v_mfma_f32_16x16x32_bf16 v[2:5], v[94:97], v[86:89], v[2:5]
	s_waitcnt lgkmcnt(3)
	v_mfma_f32_16x16x32_bf16 v[30:33], v[164:167], v[180:183], v[30:33]
	v_mfma_f32_16x16x32_bf16 v[26:29], v[168:171], v[180:183], v[26:29]
	s_waitcnt vmcnt(2)
	ds_write_b128 v190, v[236:239] offset:53264
	v_mfma_f32_16x16x32_bf16 v[22:25], v[172:175], v[180:183], v[22:25]
	v_mfma_f32_16x16x32_bf16 v[18:21], v[176:179], v[180:183], v[18:21]
	s_waitcnt vmcnt(1)
	ds_write_b128 v190, v[240:243] offset:57360
	s_waitcnt lgkmcnt(4)
	v_mfma_f32_16x16x32_bf16 v[14:17], v[164:167], v[184:187], v[14:17]
	v_mfma_f32_16x16x32_bf16 v[10:13], v[168:171], v[184:187], v[10:13]
	s_waitcnt vmcnt(0)
	ds_write_b128 v190, v[244:247] offset:61456
	v_mfma_f32_16x16x32_bf16 v[6:9], v[172:175], v[184:187], v[6:9]
	v_mfma_f32_16x16x32_bf16 v[2:5], v[176:179], v[184:187], v[2:5]
	s_waitcnt lgkmcnt(0)
	s_barrier
	ds_read_b128 v[74:77], v188 offset:49168
	ds_read_b128 v[78:81], v188 offset:49680
	ds_read_b128 v[90:93], v188 offset:53264
	ds_read_b128 v[94:97], v188 offset:53776
	ds_read_b128 v[82:85], v71 offset:32768
	ds_read_b128 v[86:89], v71 offset:34816
	s_waitcnt lgkmcnt(1)
	v_mfma_f32_16x16x32_bf16 v[30:33], v[74:77], v[82:85], v[30:33]
	ds_read_b128 v[164:167], v189 offset:49168
	ds_read_b128 v[168:171], v189 offset:49680
	v_mfma_f32_16x16x32_bf16 v[26:29], v[78:81], v[82:85], v[26:29]
	v_mfma_f32_16x16x32_bf16 v[22:25], v[90:93], v[82:85], v[22:25]
	ds_read_b128 v[172:175], v189 offset:53264
	ds_read_b128 v[176:179], v189 offset:53776
	v_mfma_f32_16x16x32_bf16 v[18:21], v[94:97], v[82:85], v[18:21]
	s_waitcnt lgkmcnt(4)
	v_mfma_f32_16x16x32_bf16 v[14:17], v[74:77], v[86:89], v[14:17]
	ds_read_b128 v[180:183], v72 offset:32768
	ds_read_b128 v[184:187], v72 offset:34816
	v_mfma_f32_16x16x32_bf16 v[10:13], v[78:81], v[86:89], v[10:13]
	v_mfma_f32_16x16x32_bf16 v[6:9], v[90:93], v[86:89], v[6:9]
	v_mfma_f32_16x16x32_bf16 v[2:5], v[94:97], v[86:89], v[2:5]
	s_waitcnt lgkmcnt(1)
	v_mfma_f32_16x16x32_bf16 v[30:33], v[164:167], v[180:183], v[30:33]
	v_mfma_f32_16x16x32_bf16 v[26:29], v[168:171], v[180:183], v[26:29]
	v_mfma_f32_16x16x32_bf16 v[22:25], v[172:175], v[180:183], v[22:25]
	v_mfma_f32_16x16x32_bf16 v[18:21], v[176:179], v[180:183], v[18:21]
	s_waitcnt lgkmcnt(0)
	v_mfma_f32_16x16x32_bf16 v[14:17], v[164:167], v[184:187], v[14:17]
	v_mfma_f32_16x16x32_bf16 v[10:13], v[168:171], v[184:187], v[10:13]
	v_mfma_f32_16x16x32_bf16 v[6:9], v[172:175], v[184:187], v[6:9]
	v_mfma_f32_16x16x32_bf16 v[2:5], v[176:179], v[184:187], v[2:5]
	s_barrier
